# v035 + leading V-fragment reads of the P.V half issued above the row-max chain
# speedup vs baseline: 1.0066x; 1.0002x over previous
; #define LAS __attribute__((address_space(3)))
; __device__ __forceinline__ float ex2(float v) { return __builtin_amdgcn_exp2f(v); }
; #define MFMA32(a, b, c) __builtin_amdgcn_mfma_f32_32x32x16_bf16((a), (b), (c), 0, 0, 0)
; #define SCHEDB() __builtin_amdgcn_sched_barrier(0)
; __device__ __forceinline__ void diff_unit(const Params& p, LAS unsigned char* lds, int b, int h, int qb, float lam) {
;     ...
; #pragma unroll
;                 for (int r = 0; r < 16; ++r) s0[r] = ex2(s0[r]);
; #pragma unroll
;                 for (int g = 0; g < 4; ++g) {
;                     const int co = ((4 * (g >> 1) + (g & 1)) ^ xv) << 4;
;                     bf16x8 vf[4];
; #pragma unroll
;                     for (int db = 0; db < 4; ++db) vf[db] = *(const LAS bf16x8*)(vb + db * 4096 + co);
;                     const bf16x8 pf = pack8((g >> 1) ? s1 : s0, 8 * (g & 1));
; #pragma unroll
;                     for (int db = 0; db < 4; ++db) O[db] = MFMA32(pf, vf[db], O[db]);
;                     L = MFMA32(pf, ones, L);
;                     if (g < 2) {
; #pragma unroll
;                         for (int r = 0; r < 8; ++r) s1[8 * g + r] = ex2(s1[8 * g + r]);
;                     }
;                     SCHEDB();
;                 }
.LBB0_283:
	v_add_u32_e32 v244, v4, v199
	ds_read_b128 v[216:219], v244 offset:32768
	v_exp_f32_e32 v5, v128
	v_exp_f32_e32 v14, v129
	v_exp_f32_e32 v15, v130
	v_exp_f32_e32 v183, v131
	v_exp_f32_e32 v184, v132
	v_exp_f32_e32 v185, v133
	v_exp_f32_e32 v186, v134
	v_exp_f32_e32 v187, v135
	v_exp_f32_e32 v188, v136
	v_exp_f32_e32 v189, v137
	v_exp_f32_e32 v209, v138
	v_exp_f32_e32 v210, v139
	v_cvt_pk_bf16_f32 v136, v5, v14
	v_cvt_pk_bf16_f32 v137, v15, v183
	v_cvt_pk_bf16_f32 v138, v184, v185
	v_cvt_pk_bf16_f32 v139, v186, v187
	s_mov_b32 s9, s8
	s_waitcnt lgkmcnt(4)
	v_mfma_f32_32x32x16_bf16 v[16:31], v[136:139], v[240:243], v[16:31]
	ds_read_b128 v[240:243], v244 offset:36864
	s_mov_b32 s10, s8
	s_mov_b32 s11, s8
	v_mov_b64_e32 v[6:7], s[8:9]
	v_mov_b64_e32 v[8:9], s[10:11]
	v_exp_f32_e32 v140, v140
	v_exp_f32_e32 v141, v141
	v_exp_f32_e32 v142, v142
	s_waitcnt lgkmcnt(4)
	v_mfma_f32_32x32x16_bf16 v[32:47], v[136:139], v[236:239], v[32:47]
	ds_read_b128 v[236:239], v244 offset:40960
	v_exp_f32_e32 v143, v143
	v_exp_f32_e32 v5, v112
	v_exp_f32_e32 v14, v113
	v_exp_f32_e32 v15, v114
	v_exp_f32_e32 v116, v116
	v_exp_f32_e32 v117, v117
	v_exp_f32_e32 v118, v118
	s_waitcnt lgkmcnt(4)
	v_mfma_f32_32x32x16_bf16 v[48:63], v[136:139], v[232:235], v[48:63]
	ds_read_b128 v[232:235], v244 offset:45056
	v_exp_f32_e32 v128, v115
	v_exp_f32_e32 v119, v119
	s_waitcnt lgkmcnt(4)
	v_mfma_f32_32x32x16_bf16 v[64:79], v[136:139], v[228:231], v[64:79]
	v_add_u32_e32 v244, v4, v200
	ds_read_b128 v[228:231], v244 offset:32768
	v_mfma_f32_32x32x16_bf16 v[80:95], v[136:139], v[6:9], v[80:95]
	v_cvt_pk_bf16_f32 v10, v188, v189
	v_cvt_pk_bf16_f32 v11, v209, v210
	v_cvt_pk_bf16_f32 v12, v140, v141
	v_cvt_pk_bf16_f32 v13, v142, v143
	v_exp_f32_e32 v120, v120
	s_waitcnt lgkmcnt(4)
	v_mfma_f32_32x32x16_bf16 v[16:31], v[10:13], v[216:219], v[16:31]
	ds_read_b128 v[216:219], v244 offset:36864
	v_exp_f32_e32 v121, v121
	v_exp_f32_e32 v122, v122
	v_exp_f32_e32 v123, v123
	v_exp_f32_e32 v124, v124
	v_exp_f32_e32 v125, v125
	v_exp_f32_e32 v126, v126
	s_waitcnt lgkmcnt(4)
	v_mfma_f32_32x32x16_bf16 v[32:47], v[10:13], v[240:243], v[32:47]
	ds_read_b128 v[240:243], v244 offset:40960
	v_exp_f32_e32 v127, v127
	s_waitcnt lgkmcnt(4)
	v_mfma_f32_32x32x16_bf16 v[48:63], v[10:13], v[236:239], v[48:63]
	ds_read_b128 v[236:239], v244 offset:45056
	s_waitcnt lgkmcnt(4)
	v_mfma_f32_32x32x16_bf16 v[64:79], v[10:13], v[232:235], v[64:79]
	v_add_u32_e32 v244, v4, v201
	ds_read_b128 v[232:235], v244 offset:32768
	v_mfma_f32_32x32x16_bf16 v[80:95], v[10:13], v[6:9], v[80:95]
	v_cvt_pk_bf16_f32 v10, v5, v14
	v_cvt_pk_bf16_f32 v11, v15, v128
	v_cvt_pk_bf16_f32 v12, v116, v117
	v_cvt_pk_bf16_f32 v13, v118, v119
	s_waitcnt lgkmcnt(4)
	s_nop 0
	v_mfma_f32_32x32x16_bf16 v[16:31], v[10:13], v[228:231], v[16:31]
	ds_read_b128 v[228:231], v244 offset:36864
	s_waitcnt lgkmcnt(4)
	v_mfma_f32_32x32x16_bf16 v[32:47], v[10:13], v[216:219], v[32:47]
	ds_read_b128 v[216:219], v244 offset:40960
	s_waitcnt lgkmcnt(4)
	v_mfma_f32_32x32x16_bf16 v[48:63], v[10:13], v[240:243], v[48:63]
	ds_read_b128 v[240:243], v244 offset:45056
	s_waitcnt lgkmcnt(4)
	v_mfma_f32_32x32x16_bf16 v[64:79], v[10:13], v[236:239], v[64:79]
	v_mfma_f32_32x32x16_bf16 v[80:95], v[10:13], v[6:9], v[80:95]
	v_add_u32_e32 v4, v4, v201
	v_cvt_pk_bf16_f32 v10, v120, v121
	v_cvt_pk_bf16_f32 v11, v122, v123
	v_cvt_pk_bf16_f32 v12, v124, v125
	v_cvt_pk_bf16_f32 v13, v126, v127
	s_waitcnt lgkmcnt(3)
	s_nop 0
	v_mfma_f32_32x32x16_bf16 v[16:31], v[10:13], v[232:235], v[16:31]
	s_waitcnt lgkmcnt(2)
	v_mfma_f32_32x32x16_bf16 v[32:47], v[10:13], v[228:231], v[32:47]
	s_waitcnt lgkmcnt(1)
	v_mfma_f32_32x32x16_bf16 v[48:63], v[10:13], v[216:219], v[48:63]
	s_waitcnt lgkmcnt(0)
	v_mfma_f32_32x32x16_bf16 v[64:79], v[10:13], v[240:243], v[64:79]
	v_mfma_f32_32x32x16_bf16 v[80:95], v[10:13], v[6:9], v[80:95]

; __device__ __forceinline__ float ex2(float v) { return __builtin_amdgcn_exp2f(v); }
; __device__ __forceinline__ int crow(int r, int h) { return (r & 3) + 8 * (r >> 2) + 4 * h; }
; #define MX3(a, b, c) __builtin_fmaxf(__builtin_fmaxf((a), (b)), (c))
; __device__ __forceinline__ void diff_unit(const Params& p, LAS unsigned char* lds, int b, int h, int qb, float lam) {
;     ...
;                 float mx;
;                 { float a0 = MX3(s0[0], s0[1], s1[0]), a1 = MX3(s0[2], s0[3], s1[1]); a0 = MX3(a0, s1[2], s1[3]);
; #pragma unroll
;                   for (int r = 4; r < 16; r += 4) { a0 = MX3(a0, s0[r], s0[r + 1]); a1 = MX3(a1, s0[r + 2], s0[r + 3]); a0 = MX3(a0, s1[r], s1[r + 1]); a1 = MX3(a1, s1[r + 2], s1[r + 3]); }
;                   mx = fmaxf(a0, a1); }
;                 { auto rr = __builtin_amdgcn_permlane32_swap(__float_as_uint(mx), __float_as_uint(mx), false, false); mx = fmaxf(__uint_as_float(rr[0]), __uint_as_float(rr[1])); }
;                 const bool first = (jt == 0);
;                 if (first || __any(mx > 8.0f)) {
;                     const float dl = first ? mx : fmaxf(mx, 0.f);
;                     m += dl;
; #pragma unroll
;                     for (int r = 0; r < 16; ++r) { s0[r] -= dl; s1[r] -= dl; }
; #pragma unroll
;                     for (int r = 0; r < 16; ++r) negm[r] = -m;
;                     if (!first) {
;                         const float alpha = ex2(-dl);
;                         int hl = hh; asm volatile("" : "+v"(hl));
; #pragma unroll
;                         for (int r = 0; r < 16; ++r) { const float a = __shfl(alpha, crow(r, hl)); L[r] *= a;
; #pragma unroll
;                             for (int db = 0; db < 4; ++db) O[db][r] *= a; }
;                     }
;                 }
.LBB0_288:
	v_add_u32_e32 v244, v4, v198
	ds_read_b128 v[240:243], v244 offset:32768
	ds_read_b128 v[236:239], v244 offset:36864
	ds_read_b128 v[232:235], v244 offset:40960
	ds_read_b128 v[228:231], v244 offset:45056
	s_nop 7
	v_max_f32_e32 v5, v129, v129
	v_max_f32_e32 v6, v128, v128
	v_max_f32_e32 v5, v6, v5
	v_max3_f32 v6, v130, v131, v113
	v_max3_f32 v5, v5, v112, v114
	v_max3_f32 v5, v5, v115, v132
	v_max3_f32 v6, v6, v134, v135
	v_max3_f32 v5, v5, v133, v116
	v_max3_f32 v6, v6, v118, v119
	v_max3_f32 v5, v5, v117, v136
	v_max3_f32 v6, v6, v138, v139
	v_max3_f32 v5, v5, v137, v120
	v_max3_f32 v6, v6, v122, v123
	v_max3_f32 v5, v5, v121, v140
	v_max3_f32 v6, v6, v142, v143
	v_max3_f32 v5, v5, v141, v124
	v_max3_f32 v6, v6, v126, v127
	v_max3_f32 v5, v5, v125, v6
	v_mov_b32_e32 v6, v5
	s_nop 1
	v_permlane32_swap_b32_e32 v5, v6
	v_max_f32_e32 v6, v6, v6
	v_max_f32_e32 v5, v5, v5
	v_max_f32_e32 v5, v5, v6
	v_cmp_lt_f32_e32 vcc, s70, v5
	s_cbranch_vccz .LBB0_283
	v_max_f32_e32 v5, v5, v5
	v_max_f32_e32 v6, 0, v5
	v_pk_add_f32 v[112:113], v[112:113], v[6:7] op_sel_hi:[1,0] neg_lo:[0,1] neg_hi:[0,1]
	v_pk_add_f32 v[114:115], v[114:115], v[6:7] op_sel_hi:[1,0] neg_lo:[0,1] neg_hi:[0,1]
	v_pk_add_f32 v[116:117], v[116:117], v[6:7] op_sel_hi:[1,0] neg_lo:[0,1] neg_hi:[0,1]
	v_pk_add_f32 v[118:119], v[118:119], v[6:7] op_sel_hi:[1,0] neg_lo:[0,1] neg_hi:[0,1]
	v_pk_add_f32 v[120:121], v[120:121], v[6:7] op_sel_hi:[1,0] neg_lo:[0,1] neg_hi:[0,1]
	v_pk_add_f32 v[122:123], v[122:123], v[6:7] op_sel_hi:[1,0] neg_lo:[0,1] neg_hi:[0,1]
	v_pk_add_f32 v[124:125], v[124:125], v[6:7] op_sel_hi:[1,0] neg_lo:[0,1] neg_hi:[0,1]
	v_pk_add_f32 v[126:127], v[126:127], v[6:7] op_sel_hi:[1,0] neg_lo:[0,1] neg_hi:[0,1]
	v_pk_add_f32 v[128:129], v[128:129], v[6:7] op_sel_hi:[1,0] neg_lo:[0,1] neg_hi:[0,1]
	v_pk_add_f32 v[130:131], v[130:131], v[6:7] op_sel_hi:[1,0] neg_lo:[0,1] neg_hi:[0,1]
	v_pk_add_f32 v[132:133], v[132:133], v[6:7] op_sel_hi:[1,0] neg_lo:[0,1] neg_hi:[0,1]
	v_pk_add_f32 v[134:135], v[134:135], v[6:7] op_sel_hi:[1,0] neg_lo:[0,1] neg_hi:[0,1]
	v_pk_add_f32 v[136:137], v[136:137], v[6:7] op_sel_hi:[1,0] neg_lo:[0,1] neg_hi:[0,1]
	v_pk_add_f32 v[138:139], v[138:139], v[6:7] op_sel_hi:[1,0] neg_lo:[0,1] neg_hi:[0,1]
	v_pk_add_f32 v[140:141], v[140:141], v[6:7] op_sel_hi:[1,0] neg_lo:[0,1] neg_hi:[0,1]
	v_pk_add_f32 v[142:143], v[142:143], v[6:7] op_sel_hi:[1,0] neg_lo:[0,1] neg_hi:[0,1]
	v_add_f32_e32 v165, v165, v6
	v_exp_f32_e64 v5, -v6
	v_mov_b32_e32 v6, v195
	v_xor_b32_e32 v96, 0x80000000, v165
	v_lshlrev_b32_e32 v13, 2, v6
	v_add_u32_e32 v14, 11, v13
	v_and_or_b32 v14, v14, 63, v194
	v_and_or_b32 v6, v13, 60, v194
	v_add_u32_e32 v10, 8, v13
	v_add_u32_e32 v11, 9, v13
	v_add_u32_e32 v12, 10, v13
	v_lshlrev_b32_e32 v183, 2, v14
	v_add_u32_e32 v14, 16, v13
	v_add_u32_e32 v15, 17, v13
	v_add_u32_e32 v184, 18, v13
	v_add_u32_e32 v185, 19, v13
	v_add_u32_e32 v186, 24, v13
	v_add_u32_e32 v187, 25, v13
	v_add_u32_e32 v188, 26, v13
	v_add_u32_e32 v13, 27, v13
	v_and_or_b32 v10, v10, 60, v194
	v_and_or_b32 v11, v11, 61, v194
	v_and_or_b32 v12, v12, 62, v194
	v_and_or_b32 v14, v14, 60, v194
	v_and_or_b32 v15, v15, 61, v194
	v_and_or_b32 v184, v184, 62, v194
	v_and_or_b32 v185, v185, 63, v194
	v_and_or_b32 v186, v186, 60, v194
	v_and_or_b32 v187, v187, 61, v194
	v_and_or_b32 v188, v188, 62, v194
	v_and_or_b32 v13, v13, 63, v194
	v_lshlrev_b32_e32 v9, 2, v6
	v_lshlrev_b32_e32 v10, 2, v10
	v_lshlrev_b32_e32 v11, 2, v11
	v_lshlrev_b32_e32 v12, 2, v12
	v_lshlrev_b32_e32 v14, 2, v14
	v_lshlrev_b32_e32 v15, 2, v15
	v_lshlrev_b32_e32 v184, 2, v184
	v_lshlrev_b32_e32 v185, 2, v185
	v_lshlrev_b32_e32 v186, 2, v186
	v_lshlrev_b32_e32 v187, 2, v187
	v_lshlrev_b32_e32 v188, 2, v188
	v_lshlrev_b32_e32 v13, 2, v13
	ds_bpermute_b32 v6, v9, v5
	ds_bpermute_b32 v7, v9, v5 offset:4
	ds_bpermute_b32 v8, v9, v5 offset:8
	ds_bpermute_b32 v9, v9, v5 offset:12
	ds_bpermute_b32 v10, v10, v5
	ds_bpermute_b32 v11, v11, v5
	ds_bpermute_b32 v12, v12, v5
	ds_bpermute_b32 v14, v14, v5
	ds_bpermute_b32 v184, v184, v5
	ds_bpermute_b32 v186, v186, v5
	ds_bpermute_b32 v188, v188, v5
	ds_bpermute_b32 v189, v13, v5
	ds_bpermute_b32 v187, v187, v5
	ds_bpermute_b32 v185, v185, v5
	ds_bpermute_b32 v15, v15, v5
	ds_bpermute_b32 v13, v183, v5
	v_mov_b32_e32 v97, v96
	v_mov_b32_e32 v98, v96
	v_mov_b32_e32 v99, v96
	v_mov_b32_e32 v100, v96
	v_mov_b32_e32 v101, v96
	v_mov_b32_e32 v102, v96
	v_mov_b32_e32 v103, v96
	v_mov_b32_e32 v104, v96
	v_mov_b32_e32 v105, v96
	v_mov_b32_e32 v106, v96
	v_mov_b32_e32 v107, v96
	v_mov_b32_e32 v108, v96
	v_mov_b32_e32 v109, v96
	v_mov_b32_e32 v110, v96
	v_mov_b32_e32 v111, v96
	s_waitcnt lgkmcnt(0)
	v_pk_mul_f32 v[30:31], v[30:31], v[188:189]
	v_pk_mul_f32 v[28:29], v[28:29], v[186:187]
	v_pk_mul_f32 v[26:27], v[26:27], v[184:185]
	v_pk_mul_f32 v[24:25], v[24:25], v[14:15]
	v_pk_mul_f32 v[22:23], v[22:23], v[12:13]
	v_pk_mul_f32 v[20:21], v[20:21], v[10:11]
	v_pk_mul_f32 v[18:19], v[18:19], v[8:9]
	v_pk_mul_f32 v[16:17], v[16:17], v[6:7]
	v_pk_mul_f32 v[46:47], v[46:47], v[188:189]
	v_pk_mul_f32 v[44:45], v[44:45], v[186:187]
	v_pk_mul_f32 v[42:43], v[42:43], v[184:185]
	v_pk_mul_f32 v[40:41], v[40:41], v[14:15]
	v_pk_mul_f32 v[38:39], v[38:39], v[12:13]
	v_pk_mul_f32 v[36:37], v[36:37], v[10:11]
	v_pk_mul_f32 v[34:35], v[34:35], v[8:9]
	v_pk_mul_f32 v[32:33], v[32:33], v[6:7]
	v_pk_mul_f32 v[62:63], v[62:63], v[188:189]
	v_pk_mul_f32 v[60:61], v[60:61], v[186:187]
	v_pk_mul_f32 v[58:59], v[58:59], v[184:185]
	v_pk_mul_f32 v[56:57], v[56:57], v[14:15]
	v_pk_mul_f32 v[54:55], v[54:55], v[12:13]
	v_pk_mul_f32 v[52:53], v[52:53], v[10:11]
	v_pk_mul_f32 v[50:51], v[50:51], v[8:9]
	v_pk_mul_f32 v[48:49], v[48:49], v[6:7]
	v_pk_mul_f32 v[78:79], v[78:79], v[188:189]
	v_pk_mul_f32 v[76:77], v[76:77], v[186:187]
	v_pk_mul_f32 v[74:75], v[74:75], v[184:185]
	v_pk_mul_f32 v[72:73], v[72:73], v[14:15]
	v_pk_mul_f32 v[70:71], v[70:71], v[12:13]
	v_pk_mul_f32 v[68:69], v[68:69], v[10:11]
	v_pk_mul_f32 v[66:67], v[66:67], v[8:9]
	v_pk_mul_f32 v[64:65], v[64:65], v[6:7]
	v_pk_mul_f32 v[94:95], v[94:95], v[188:189]
	v_pk_mul_f32 v[92:93], v[92:93], v[186:187]
	v_pk_mul_f32 v[90:91], v[90:91], v[184:185]
	v_pk_mul_f32 v[88:89], v[88:89], v[14:15]
	v_pk_mul_f32 v[86:87], v[86:87], v[12:13]
	v_pk_mul_f32 v[84:85], v[84:85], v[10:11]
	v_pk_mul_f32 v[82:83], v[82:83], v[8:9]
	v_pk_mul_f32 v[80:81], v[80:81], v[6:7]
	s_branch .LBB0_283

; #define LAS __attribute__((address_space(3)))
; __device__ __forceinline__ float ex2(float v) { return __builtin_amdgcn_exp2f(v); }
; #define MFMA32(a, b, c) __builtin_amdgcn_mfma_f32_32x32x16_bf16((a), (b), (c), 0, 0, 0)
; #define SCHEDB() __builtin_amdgcn_sched_barrier(0)
; __device__ __forceinline__ void diff_unit(const Params& p, LAS unsigned char* lds, int b, int h, int qb, float lam) {
;     ...
; #pragma unroll
;                 for (int r = 0; r < 16; ++r) s0[r] = ex2(s0[r]);
; #pragma unroll
;                 for (int g = 0; g < 4; ++g) {
;                     const int co = ((4 * (g >> 1) + (g & 1)) ^ xv) << 4;
;                     bf16x8 vf[4];
; #pragma unroll
;                     for (int db = 0; db < 4; ++db) vf[db] = *(const LAS bf16x8*)(vb + db * 4096 + co);
;                     const bf16x8 pf = pack8((g >> 1) ? s1 : s0, 8 * (g & 1));
; #pragma unroll
;                     for (int db = 0; db < 4; ++db) O[db] = MFMA32(pf, vf[db], O[db]);
;                     L = MFMA32(pf, ones, L);
;                     if (g < 2) {
; #pragma unroll
;                         for (int r = 0; r < 8; ++r) s1[8 * g + r] = ex2(s1[8 * g + r]);
;                     }
;                     SCHEDB();
;                 }
.LBB0_303:
	v_add_u32_e32 v244, v0, v198
	ds_read_b128 v[228:231], v244 offset:45056
	v_add_u32_e32 v244, v0, v199
	ds_read_b128 v[184:187], v244 offset:32768
	ds_read_b128 v[176:179], v244 offset:36864
	v_exp_f32_e32 v128, v128
	v_exp_f32_e32 v129, v129
	v_exp_f32_e32 v130, v130
	v_exp_f32_e32 v131, v131
	v_exp_f32_e32 v132, v132
	v_exp_f32_e32 v133, v133
	v_exp_f32_e32 v134, v134
	v_exp_f32_e32 v135, v135
	v_cvt_pk_bf16_f32 v128, v128, v129
	v_cvt_pk_bf16_f32 v129, v130, v131
	v_cvt_pk_bf16_f32 v130, v132, v133
	v_cvt_pk_bf16_f32 v131, v134, v135
	s_waitcnt lgkmcnt(5)
	s_nop 0
	v_mfma_f32_32x32x16_bf16 v[16:31], v[128:131], v[240:243], v[16:31]
	ds_read_b128 v[240:243], v244 offset:40960
	s_mov_b32 s10, s8
	s_mov_b32 s11, s8
	s_mov_b32 s9, s8
	v_exp_f32_e32 v136, v136
	v_exp_f32_e32 v137, v137
	v_exp_f32_e32 v138, v138
	s_waitcnt lgkmcnt(5)
	v_mfma_f32_32x32x16_bf16 v[32:47], v[128:131], v[236:239], v[32:47]
	ds_read_b128 v[236:239], v244 offset:45056
	v_exp_f32_e32 v139, v139
	v_exp_f32_e32 v140, v140
	v_exp_f32_e32 v141, v141
	v_exp_f32_e32 v142, v142
	v_exp_f32_e32 v143, v143
	v_exp_f32_e32 v213, v112
	s_waitcnt lgkmcnt(5)
	v_mfma_f32_32x32x16_bf16 v[48:63], v[128:131], v[232:235], v[48:63]
	v_add_u32_e32 v244, v0, v200
	ds_read_b128 v[232:235], v244 offset:32768
	v_mov_b64_e32 v[134:135], s[10:11]
	v_mov_b64_e32 v[132:133], s[8:9]
	v_exp_f32_e32 v218, v117
	v_exp_f32_e32 v219, v118
	v_exp_f32_e32 v220, v119
	s_waitcnt lgkmcnt(5)
	v_mfma_f32_32x32x16_bf16 v[64:79], v[128:131], v[228:231], v[64:79]
	ds_read_b128 v[228:231], v244 offset:36864
	v_exp_f32_e32 v214, v113
	v_exp_f32_e32 v215, v114
	v_exp_f32_e32 v216, v115
	v_exp_f32_e32 v217, v116
	v_mfma_f32_32x32x16_bf16 v[80:95], v[128:131], v[132:135], v[80:95]
	v_cvt_pk_bf16_f32 v112, v136, v137
	v_cvt_pk_bf16_f32 v113, v138, v139
	v_cvt_pk_bf16_f32 v114, v140, v141
	v_cvt_pk_bf16_f32 v115, v142, v143
	s_waitcnt lgkmcnt(5)
	s_nop 0
	v_mfma_f32_32x32x16_bf16 v[16:31], v[112:115], v[184:187], v[16:31]
	ds_read_b128 v[184:187], v244 offset:40960
	v_exp_f32_e32 v124, v124
	v_exp_f32_e32 v125, v125
	v_exp_f32_e32 v126, v126
	v_exp_f32_e32 v127, v127
	s_waitcnt lgkmcnt(5)
	v_mfma_f32_32x32x16_bf16 v[32:47], v[112:115], v[176:179], v[32:47]
	ds_read_b128 v[176:179], v244 offset:45056
	s_waitcnt lgkmcnt(5)
	v_mfma_f32_32x32x16_bf16 v[48:63], v[112:115], v[240:243], v[48:63]
	v_add_u32_e32 v244, v0, v201
	ds_read_b128 v[240:243], v244 offset:32768
	s_waitcnt lgkmcnt(5)
	v_mfma_f32_32x32x16_bf16 v[64:79], v[112:115], v[236:239], v[64:79]
	ds_read_b128 v[236:239], v244 offset:36864
	v_exp_f32_e32 v128, v120
	v_exp_f32_e32 v129, v121
	v_exp_f32_e32 v130, v122
	v_exp_f32_e32 v131, v123
	v_mfma_f32_32x32x16_bf16 v[80:95], v[112:115], v[132:135], v[80:95]
	v_cvt_pk_bf16_f32 v112, v213, v214
	v_cvt_pk_bf16_f32 v113, v215, v216
	v_cvt_pk_bf16_f32 v114, v217, v218
	v_cvt_pk_bf16_f32 v115, v219, v220
	s_waitcnt lgkmcnt(5)
	s_nop 0
	v_mfma_f32_32x32x16_bf16 v[16:31], v[112:115], v[232:235], v[16:31]
	ds_read_b128 v[232:235], v244 offset:40960
	s_waitcnt lgkmcnt(5)
	v_mfma_f32_32x32x16_bf16 v[32:47], v[112:115], v[228:231], v[32:47]
	ds_read_b128 v[228:231], v244 offset:45056
	s_waitcnt lgkmcnt(5)
	v_mfma_f32_32x32x16_bf16 v[48:63], v[112:115], v[184:187], v[48:63]
	s_waitcnt lgkmcnt(4)
	v_mfma_f32_32x32x16_bf16 v[64:79], v[112:115], v[176:179], v[64:79]
	v_mfma_f32_32x32x16_bf16 v[80:95], v[112:115], v[132:135], v[80:95]
	v_add_u32_e32 v0, v0, v201
	v_cvt_pk_bf16_f32 v112, v128, v129
	v_cvt_pk_bf16_f32 v113, v130, v131
	v_cvt_pk_bf16_f32 v114, v124, v125
	v_cvt_pk_bf16_f32 v115, v126, v127
	s_waitcnt lgkmcnt(3)
	s_nop 0
	v_mfma_f32_32x32x16_bf16 v[16:31], v[112:115], v[240:243], v[16:31]
	s_waitcnt lgkmcnt(2)
	v_mfma_f32_32x32x16_bf16 v[32:47], v[112:115], v[236:239], v[32:47]
	s_waitcnt lgkmcnt(1)
	v_mfma_f32_32x32x16_bf16 v[48:63], v[112:115], v[232:235], v[48:63]
	s_waitcnt lgkmcnt(0)
	v_mfma_f32_32x32x16_bf16 v[64:79], v[112:115], v[228:231], v[64:79]
	v_mfma_f32_32x32x16_bf16 v[80:95], v[112:115], v[132:135], v[80:95]

; __device__ __forceinline__ float ex2(float v) { return __builtin_amdgcn_exp2f(v); }
; __device__ __forceinline__ int crow(int r, int h) { return (r & 3) + 8 * (r >> 2) + 4 * h; }
; #define MX3(a, b, c) __builtin_fmaxf(__builtin_fmaxf((a), (b)), (c))
; __device__ __forceinline__ void diff_unit(const Params& p, LAS unsigned char* lds, int b, int h, int qb, float lam) {
;     ...
;                 float mx;
;                 { float a0 = MX3(s0[0], s0[1], s1[0]), a1 = MX3(s0[2], s0[3], s1[1]); a0 = MX3(a0, s1[2], s1[3]);
; #pragma unroll
;                   for (int r = 4; r < 16; r += 4) { a0 = MX3(a0, s0[r], s0[r + 1]); a1 = MX3(a1, s0[r + 2], s0[r + 3]); a0 = MX3(a0, s1[r], s1[r + 1]); a1 = MX3(a1, s1[r + 2], s1[r + 3]); }
;                   mx = fmaxf(a0, a1); }
;                 { auto rr = __builtin_amdgcn_permlane32_swap(__float_as_uint(mx), __float_as_uint(mx), false, false); mx = fmaxf(__uint_as_float(rr[0]), __uint_as_float(rr[1])); }
;                 const bool first = (jt == 0);
;                 if (first || __any(mx > 8.0f)) {
;                     const float dl = first ? mx : fmaxf(mx, 0.f);
;                     m += dl;
; #pragma unroll
;                     for (int r = 0; r < 16; ++r) { s0[r] -= dl; s1[r] -= dl; }
; #pragma unroll
;                     for (int r = 0; r < 16; ++r) negm[r] = -m;
;                     if (!first) {
;                         const float alpha = ex2(-dl);
;                         int hl = hh; asm volatile("" : "+v"(hl));
; #pragma unroll
;                         for (int r = 0; r < 16; ++r) { const float a = __shfl(alpha, crow(r, hl)); L[r] *= a;
; #pragma unroll
;                             for (int db = 0; db < 4; ++db) O[db][r] *= a; }
;                     }
;                 }
.LBB0_308:
	v_add_u32_e32 v244, v0, v198
	ds_read_b128 v[240:243], v244 offset:32768
	ds_read_b128 v[236:239], v244 offset:36864
	ds_read_b128 v[232:235], v244 offset:40960
	s_nop 7
	v_max_f32_e32 v213, v129, v129
	v_max_f32_e32 v214, v128, v128
	v_max_f32_e32 v213, v214, v213
	v_max3_f32 v214, v130, v131, v113
	v_max3_f32 v213, v213, v112, v114
	v_max3_f32 v213, v213, v115, v132
	v_max3_f32 v214, v214, v134, v135
	v_max3_f32 v213, v213, v133, v116
	v_max3_f32 v214, v214, v118, v119
	v_max3_f32 v213, v213, v117, v136
	v_max3_f32 v214, v214, v138, v139
	v_max3_f32 v213, v213, v137, v120
	v_max3_f32 v214, v214, v122, v123
	v_max3_f32 v213, v213, v121, v140
	v_max3_f32 v214, v214, v142, v143
	v_max3_f32 v213, v213, v141, v124
	v_max3_f32 v214, v214, v126, v127
	v_max3_f32 v213, v213, v125, v214
	v_mov_b32_e32 v214, v213
	s_nop 1
	v_permlane32_swap_b32_e32 v213, v214
	v_max_f32_e32 v214, v214, v214
	v_max_f32_e32 v213, v213, v213
	v_max_f32_e32 v213, v213, v214
	v_cmp_lt_f32_e32 vcc, s70, v213
	s_cbranch_vccz .LBB0_303
	v_max_f32_e32 v96, v213, v213
	v_max_f32_e32 v214, 0, v96
	v_pk_add_f32 v[112:113], v[112:113], v[214:215] op_sel_hi:[1,0] neg_lo:[0,1] neg_hi:[0,1]
	v_pk_add_f32 v[114:115], v[114:115], v[214:215] op_sel_hi:[1,0] neg_lo:[0,1] neg_hi:[0,1]
	v_pk_add_f32 v[116:117], v[116:117], v[214:215] op_sel_hi:[1,0] neg_lo:[0,1] neg_hi:[0,1]
	v_pk_add_f32 v[118:119], v[118:119], v[214:215] op_sel_hi:[1,0] neg_lo:[0,1] neg_hi:[0,1]
	v_pk_add_f32 v[120:121], v[120:121], v[214:215] op_sel_hi:[1,0] neg_lo:[0,1] neg_hi:[0,1]
	v_pk_add_f32 v[122:123], v[122:123], v[214:215] op_sel_hi:[1,0] neg_lo:[0,1] neg_hi:[0,1]
	v_pk_add_f32 v[124:125], v[124:125], v[214:215] op_sel_hi:[1,0] neg_lo:[0,1] neg_hi:[0,1]
	v_pk_add_f32 v[126:127], v[126:127], v[214:215] op_sel_hi:[1,0] neg_lo:[0,1] neg_hi:[0,1]
	v_pk_add_f32 v[128:129], v[128:129], v[214:215] op_sel_hi:[1,0] neg_lo:[0,1] neg_hi:[0,1]
	v_pk_add_f32 v[130:131], v[130:131], v[214:215] op_sel_hi:[1,0] neg_lo:[0,1] neg_hi:[0,1]
	v_pk_add_f32 v[132:133], v[132:133], v[214:215] op_sel_hi:[1,0] neg_lo:[0,1] neg_hi:[0,1]
	v_pk_add_f32 v[134:135], v[134:135], v[214:215] op_sel_hi:[1,0] neg_lo:[0,1] neg_hi:[0,1]
	v_pk_add_f32 v[136:137], v[136:137], v[214:215] op_sel_hi:[1,0] neg_lo:[0,1] neg_hi:[0,1]
	v_pk_add_f32 v[138:139], v[138:139], v[214:215] op_sel_hi:[1,0] neg_lo:[0,1] neg_hi:[0,1]
	v_pk_add_f32 v[140:141], v[140:141], v[214:215] op_sel_hi:[1,0] neg_lo:[0,1] neg_hi:[0,1]
	v_pk_add_f32 v[142:143], v[142:143], v[214:215] op_sel_hi:[1,0] neg_lo:[0,1] neg_hi:[0,1]
	v_add_f32_e32 v212, v212, v214
	v_exp_f32_e64 v213, -v214
	v_mov_b32_e32 v214, v195
	v_xor_b32_e32 v96, 0x80000000, v212
	v_lshlrev_b32_e32 v221, 2, v214
	v_add_u32_e32 v222, 11, v221
	v_and_or_b32 v222, v222, 63, v194
	v_and_or_b32 v214, v221, 60, v194
	v_add_u32_e32 v218, 8, v221
	v_add_u32_e32 v219, 9, v221
	v_add_u32_e32 v220, 10, v221
	v_lshlrev_b32_e32 v230, 2, v222
	v_add_u32_e32 v222, 16, v221
	v_add_u32_e32 v223, 17, v221
	v_add_u32_e32 v224, 18, v221
	v_add_u32_e32 v225, 19, v221
	v_add_u32_e32 v226, 24, v221
	v_add_u32_e32 v227, 25, v221
	v_add_u32_e32 v228, 26, v221
	v_add_u32_e32 v221, 27, v221
	v_and_or_b32 v218, v218, 60, v194
	v_and_or_b32 v219, v219, 61, v194
	v_and_or_b32 v220, v220, 62, v194
	v_and_or_b32 v222, v222, 60, v194
	v_and_or_b32 v223, v223, 61, v194
	v_and_or_b32 v224, v224, 62, v194
	v_and_or_b32 v225, v225, 63, v194
	v_and_or_b32 v226, v226, 60, v194
	v_and_or_b32 v227, v227, 61, v194
	v_and_or_b32 v228, v228, 62, v194
	v_and_or_b32 v221, v221, 63, v194
	v_lshlrev_b32_e32 v217, 2, v214
	v_lshlrev_b32_e32 v218, 2, v218
	v_lshlrev_b32_e32 v219, 2, v219
	v_lshlrev_b32_e32 v220, 2, v220
	v_lshlrev_b32_e32 v222, 2, v222
	v_lshlrev_b32_e32 v223, 2, v223
	v_lshlrev_b32_e32 v224, 2, v224
	v_lshlrev_b32_e32 v225, 2, v225
	v_lshlrev_b32_e32 v226, 2, v226
	v_lshlrev_b32_e32 v227, 2, v227
	v_lshlrev_b32_e32 v228, 2, v228
	v_lshlrev_b32_e32 v221, 2, v221
	ds_bpermute_b32 v214, v217, v213
	ds_bpermute_b32 v215, v217, v213 offset:4
	ds_bpermute_b32 v216, v217, v213 offset:8
	ds_bpermute_b32 v217, v217, v213 offset:12
	ds_bpermute_b32 v218, v218, v213
	ds_bpermute_b32 v219, v219, v213
	ds_bpermute_b32 v220, v220, v213
	ds_bpermute_b32 v222, v222, v213
	ds_bpermute_b32 v224, v224, v213
	ds_bpermute_b32 v226, v226, v213
	ds_bpermute_b32 v228, v228, v213
	ds_bpermute_b32 v229, v221, v213
	ds_bpermute_b32 v227, v227, v213
	ds_bpermute_b32 v225, v225, v213
	ds_bpermute_b32 v223, v223, v213
	ds_bpermute_b32 v221, v230, v213
	v_mov_b32_e32 v97, v96
	v_mov_b32_e32 v98, v96
	v_mov_b32_e32 v99, v96
	v_mov_b32_e32 v100, v96
	v_mov_b32_e32 v101, v96
	v_mov_b32_e32 v102, v96
	v_mov_b32_e32 v103, v96
	v_mov_b32_e32 v104, v96
	v_mov_b32_e32 v105, v96
	v_mov_b32_e32 v106, v96
	v_mov_b32_e32 v107, v96
	v_mov_b32_e32 v108, v96
	v_mov_b32_e32 v109, v96
	v_mov_b32_e32 v110, v96
	v_mov_b32_e32 v111, v96
	s_waitcnt lgkmcnt(0)
	v_pk_mul_f32 v[30:31], v[30:31], v[228:229]
	v_pk_mul_f32 v[28:29], v[28:29], v[226:227]
	v_pk_mul_f32 v[26:27], v[26:27], v[224:225]
	v_pk_mul_f32 v[24:25], v[24:25], v[222:223]
	v_pk_mul_f32 v[22:23], v[22:23], v[220:221]
	v_pk_mul_f32 v[20:21], v[20:21], v[218:219]
	v_pk_mul_f32 v[18:19], v[18:19], v[216:217]
	v_pk_mul_f32 v[16:17], v[16:17], v[214:215]
	v_pk_mul_f32 v[46:47], v[46:47], v[228:229]
	v_pk_mul_f32 v[44:45], v[44:45], v[226:227]
	v_pk_mul_f32 v[42:43], v[42:43], v[224:225]
	v_pk_mul_f32 v[40:41], v[40:41], v[222:223]
	v_pk_mul_f32 v[38:39], v[38:39], v[220:221]
	v_pk_mul_f32 v[36:37], v[36:37], v[218:219]
	v_pk_mul_f32 v[34:35], v[34:35], v[216:217]
	v_pk_mul_f32 v[32:33], v[32:33], v[214:215]
	v_pk_mul_f32 v[62:63], v[62:63], v[228:229]
	v_pk_mul_f32 v[60:61], v[60:61], v[226:227]
	v_pk_mul_f32 v[58:59], v[58:59], v[224:225]
	v_pk_mul_f32 v[56:57], v[56:57], v[222:223]
	v_pk_mul_f32 v[54:55], v[54:55], v[220:221]
	v_pk_mul_f32 v[52:53], v[52:53], v[218:219]
	v_pk_mul_f32 v[50:51], v[50:51], v[216:217]
	v_pk_mul_f32 v[48:49], v[48:49], v[214:215]
	v_pk_mul_f32 v[78:79], v[78:79], v[228:229]
	v_pk_mul_f32 v[76:77], v[76:77], v[226:227]
	v_pk_mul_f32 v[74:75], v[74:75], v[224:225]
	v_pk_mul_f32 v[72:73], v[72:73], v[222:223]
	v_pk_mul_f32 v[70:71], v[70:71], v[220:221]
	v_pk_mul_f32 v[68:69], v[68:69], v[218:219]
	v_pk_mul_f32 v[66:67], v[66:67], v[216:217]
	v_pk_mul_f32 v[64:65], v[64:65], v[214:215]
	v_pk_mul_f32 v[94:95], v[94:95], v[228:229]
	v_pk_mul_f32 v[92:93], v[92:93], v[226:227]
	v_pk_mul_f32 v[90:91], v[90:91], v[224:225]
	v_pk_mul_f32 v[88:89], v[88:89], v[222:223]
	v_pk_mul_f32 v[86:87], v[86:87], v[220:221]
	v_pk_mul_f32 v[84:85], v[84:85], v[218:219]
	v_pk_mul_f32 v[82:83], v[82:83], v[216:217]
	v_pk_mul_f32 v[80:81], v[80:81], v[214:215]
	s_branch .LBB0_303
